# P1 epilogue: straight-line per-mode code for plain/silu/sigmoid tiles + prefetched decay loads for gla q/k tiles
# speedup vs baseline: 1.0054x; 1.0054x over previous
; DEV u32x2 pk4(f32x4 v) { u32x2 r = {pk_bf16(v[0], v[1]), pk_bf16(v[2], v[3])}; return r; }
;   DEV void operator()(f32x4 (&acc)[2][2][4][2], int brow, int bcol, int wr, int wc, int fr, int fq) const {
; #pragma unroll
;     for (int ai = 0; ai < 2; ++ai)
; #pragma unroll
;       for (int m = 0; m < 4; ++m) {
;         const int rl = ai * 128 + wr * 64 + m * 16 + fr, tok = brow + rl;
; #pragma unroll
;         for (int bj = 0; bj < 2; ++bj)
; #pragma unroll
;           for (int n = 0; n < 2; ++n) {
;             const int cl = bj * 128 + wc * 32 + n * 16 + fq * 4, lc = bcol - segstart + cl;
;             f32x4 v = acc[ai][bj][m][n];
;             if (mode == 0) {
;               tile_put4(rl, cl, pk4(v * scale));
.LBB0_1580:
	s_or_b64 exec, exec, s[18:19]
	s_cmp_gt_i32 s37, 2
	s_cbranch_scc1 .Lepi_orig34
	v_and_b32_e32 v128, 15, v198
	v_bfe_u32 v129, v198, 4, 2
	v_bfe_u32 v130, v198, 6, 2
	v_lshrrev_b32_e32 v131, 8, v198
	v_lshl_add_u32 v132, v131, 6, v128
	v_lshlrev_b32_e32 v132, 9, v132
	v_and_b32_e32 v133, 1, v129
	v_lshl_add_u32 v132, v133, 3, v132
	v_lshrrev_b32_e32 v133, 1, v129
	v_lshl_add_u32 v133, v130, 2, v133
	v_xor_b32_e32 v133, v133, v128
	v_lshl_add_u32 v134, v133, 4, v132
	v_xor_b32_e32 v133, 2, v133
	v_lshl_add_u32 v135, v133, 4, v132
	v_add_u32_e32 v136, 0x10000, v134
	v_add_u32_e32 v137, 0x10000, v135
	s_mov_b32 s13, s12
	s_cmp_eq_u32 s37, 1
	s_cbranch_scc1 .Lepi_lean_silu
	s_cmp_eq_u32 s37, 2
	s_cbranch_scc1 .Lepi_lean_sigm
	v_pk_mul_f32 v[124:125], v[124:125], s[12:13]
	v_pk_mul_f32 v[126:127], v[126:127], s[12:13]
	v_cvt_pk_bf16_f32 v124, v124, v125
	v_cvt_pk_bf16_f32 v125, v126, v127
	ds_write_b64 v134, v[124:125]
	v_pk_mul_f32 v[120:121], v[120:121], s[12:13]
	v_pk_mul_f32 v[122:123], v[122:123], s[12:13]
	v_cvt_pk_bf16_f32 v120, v120, v121
	v_cvt_pk_bf16_f32 v121, v122, v123
	ds_write_b64 v135, v[120:121]
	v_pk_mul_f32 v[116:117], v[116:117], s[12:13]
	v_pk_mul_f32 v[118:119], v[118:119], s[12:13]
	v_cvt_pk_bf16_f32 v116, v116, v117
	v_cvt_pk_bf16_f32 v117, v118, v119
	ds_write_b64 v134, v[116:117] offset:256
	v_pk_mul_f32 v[112:113], v[112:113], s[12:13]
	v_pk_mul_f32 v[114:115], v[114:115], s[12:13]
	v_cvt_pk_bf16_f32 v112, v112, v113
	v_cvt_pk_bf16_f32 v113, v114, v115
	ds_write_b64 v135, v[112:113] offset:256
	v_pk_mul_f32 v[108:109], v[108:109], s[12:13]
	v_pk_mul_f32 v[110:111], v[110:111], s[12:13]
	v_cvt_pk_bf16_f32 v108, v108, v109
	v_cvt_pk_bf16_f32 v109, v110, v111
	ds_write_b64 v134, v[108:109] offset:8448
	v_pk_mul_f32 v[104:105], v[104:105], s[12:13]
	v_pk_mul_f32 v[106:107], v[106:107], s[12:13]
	v_cvt_pk_bf16_f32 v104, v104, v105
	v_cvt_pk_bf16_f32 v105, v106, v107
	ds_write_b64 v135, v[104:105] offset:8448
	v_pk_mul_f32 v[100:101], v[100:101], s[12:13]
	v_pk_mul_f32 v[102:103], v[102:103], s[12:13]
	v_cvt_pk_bf16_f32 v100, v100, v101
	v_cvt_pk_bf16_f32 v101, v102, v103
	ds_write_b64 v134, v[100:101] offset:8192
	v_pk_mul_f32 v[96:97], v[96:97], s[12:13]
	v_pk_mul_f32 v[98:99], v[98:99], s[12:13]
	v_cvt_pk_bf16_f32 v96, v96, v97
	v_cvt_pk_bf16_f32 v97, v98, v99
	ds_write_b64 v135, v[96:97] offset:8192
	v_pk_mul_f32 v[92:93], v[92:93], s[12:13]
	v_pk_mul_f32 v[94:95], v[94:95], s[12:13]
	v_cvt_pk_bf16_f32 v92, v92, v93
	v_cvt_pk_bf16_f32 v93, v94, v95
	ds_write_b64 v134, v[92:93] offset:16384
	v_pk_mul_f32 v[88:89], v[88:89], s[12:13]
	v_pk_mul_f32 v[90:91], v[90:91], s[12:13]
	v_cvt_pk_bf16_f32 v88, v88, v89
	v_cvt_pk_bf16_f32 v89, v90, v91
	ds_write_b64 v135, v[88:89] offset:16384
	v_pk_mul_f32 v[84:85], v[84:85], s[12:13]
	v_pk_mul_f32 v[86:87], v[86:87], s[12:13]
	v_cvt_pk_bf16_f32 v84, v84, v85
	v_cvt_pk_bf16_f32 v85, v86, v87
	ds_write_b64 v134, v[84:85] offset:16640
	v_pk_mul_f32 v[80:81], v[80:81], s[12:13]
	v_pk_mul_f32 v[82:83], v[82:83], s[12:13]
	v_cvt_pk_bf16_f32 v80, v80, v81
	v_cvt_pk_bf16_f32 v81, v82, v83
	ds_write_b64 v135, v[80:81] offset:16640
	v_pk_mul_f32 v[76:77], v[76:77], s[12:13]
	v_pk_mul_f32 v[78:79], v[78:79], s[12:13]
	v_cvt_pk_bf16_f32 v76, v76, v77
	v_cvt_pk_bf16_f32 v77, v78, v79
	ds_write_b64 v134, v[76:77] offset:24832
	v_pk_mul_f32 v[72:73], v[72:73], s[12:13]
	v_pk_mul_f32 v[74:75], v[74:75], s[12:13]
	v_cvt_pk_bf16_f32 v72, v72, v73
	v_cvt_pk_bf16_f32 v73, v74, v75
	ds_write_b64 v135, v[72:73] offset:24832
	v_pk_mul_f32 v[68:69], v[68:69], s[12:13]
	v_pk_mul_f32 v[70:71], v[70:71], s[12:13]
	v_cvt_pk_bf16_f32 v68, v68, v69
	v_cvt_pk_bf16_f32 v69, v70, v71
	ds_write_b64 v134, v[68:69] offset:24576
	v_pk_mul_f32 v[64:65], v[64:65], s[12:13]
	v_pk_mul_f32 v[66:67], v[66:67], s[12:13]
	v_cvt_pk_bf16_f32 v64, v64, v65
	v_cvt_pk_bf16_f32 v65, v66, v67
	ds_write_b64 v135, v[64:65] offset:24576
	v_pk_mul_f32 v[60:61], v[60:61], s[12:13]
	v_pk_mul_f32 v[62:63], v[62:63], s[12:13]
	v_cvt_pk_bf16_f32 v60, v60, v61
	v_cvt_pk_bf16_f32 v61, v62, v63
	ds_write_b64 v136, v[60:61]
	v_pk_mul_f32 v[56:57], v[56:57], s[12:13]
	v_pk_mul_f32 v[58:59], v[58:59], s[12:13]
	v_cvt_pk_bf16_f32 v56, v56, v57
	v_cvt_pk_bf16_f32 v57, v58, v59
	ds_write_b64 v137, v[56:57]
	v_pk_mul_f32 v[52:53], v[52:53], s[12:13]
	v_pk_mul_f32 v[54:55], v[54:55], s[12:13]
	v_cvt_pk_bf16_f32 v52, v52, v53
	v_cvt_pk_bf16_f32 v53, v54, v55
	ds_write_b64 v136, v[52:53] offset:256
	v_pk_mul_f32 v[48:49], v[48:49], s[12:13]
	v_pk_mul_f32 v[50:51], v[50:51], s[12:13]
	v_cvt_pk_bf16_f32 v48, v48, v49
	v_cvt_pk_bf16_f32 v49, v50, v51
	ds_write_b64 v137, v[48:49] offset:256
	v_pk_mul_f32 v[44:45], v[44:45], s[12:13]
	v_pk_mul_f32 v[46:47], v[46:47], s[12:13]
	v_cvt_pk_bf16_f32 v44, v44, v45
	v_cvt_pk_bf16_f32 v45, v46, v47
	ds_write_b64 v136, v[44:45] offset:8448
	v_pk_mul_f32 v[40:41], v[40:41], s[12:13]
	v_pk_mul_f32 v[42:43], v[42:43], s[12:13]
	v_cvt_pk_bf16_f32 v40, v40, v41
	v_cvt_pk_bf16_f32 v41, v42, v43
	ds_write_b64 v137, v[40:41] offset:8448
	v_pk_mul_f32 v[36:37], v[36:37], s[12:13]
	v_pk_mul_f32 v[38:39], v[38:39], s[12:13]
	v_cvt_pk_bf16_f32 v36, v36, v37
	v_cvt_pk_bf16_f32 v37, v38, v39
	ds_write_b64 v136, v[36:37] offset:8192
	v_pk_mul_f32 v[32:33], v[32:33], s[12:13]
	v_pk_mul_f32 v[34:35], v[34:35], s[12:13]
	v_cvt_pk_bf16_f32 v32, v32, v33
	v_cvt_pk_bf16_f32 v33, v34, v35
	ds_write_b64 v137, v[32:33] offset:8192
	v_pk_mul_f32 v[28:29], v[28:29], s[12:13]
	v_pk_mul_f32 v[30:31], v[30:31], s[12:13]
	v_cvt_pk_bf16_f32 v28, v28, v29
	v_cvt_pk_bf16_f32 v29, v30, v31
	ds_write_b64 v136, v[28:29] offset:16384
	v_pk_mul_f32 v[24:25], v[24:25], s[12:13]
	v_pk_mul_f32 v[26:27], v[26:27], s[12:13]
	v_cvt_pk_bf16_f32 v24, v24, v25
	v_cvt_pk_bf16_f32 v25, v26, v27
	ds_write_b64 v137, v[24:25] offset:16384
	v_pk_mul_f32 v[20:21], v[20:21], s[12:13]
	v_pk_mul_f32 v[22:23], v[22:23], s[12:13]
	v_cvt_pk_bf16_f32 v20, v20, v21
	v_cvt_pk_bf16_f32 v21, v22, v23
	ds_write_b64 v136, v[20:21] offset:16640
	v_pk_mul_f32 v[16:17], v[16:17], s[12:13]
	v_pk_mul_f32 v[18:19], v[18:19], s[12:13]
	v_cvt_pk_bf16_f32 v16, v16, v17
	v_cvt_pk_bf16_f32 v17, v18, v19
	ds_write_b64 v137, v[16:17] offset:16640
	v_pk_mul_f32 v[12:13], v[12:13], s[12:13]
	v_pk_mul_f32 v[14:15], v[14:15], s[12:13]
	v_cvt_pk_bf16_f32 v12, v12, v13
	v_cvt_pk_bf16_f32 v13, v14, v15
	ds_write_b64 v136, v[12:13] offset:24832
	v_pk_mul_f32 v[8:9], v[8:9], s[12:13]
	v_pk_mul_f32 v[10:11], v[10:11], s[12:13]
	v_cvt_pk_bf16_f32 v8, v8, v9
	v_cvt_pk_bf16_f32 v9, v10, v11
	ds_write_b64 v137, v[8:9] offset:24832
	v_pk_mul_f32 v[4:5], v[4:5], s[12:13]
	v_pk_mul_f32 v[6:7], v[6:7], s[12:13]
	v_cvt_pk_bf16_f32 v4, v4, v5
	v_cvt_pk_bf16_f32 v5, v6, v7
	ds_write_b64 v136, v[4:5] offset:24576
	v_pk_mul_f32 v[0:1], v[0:1], s[12:13]
	v_pk_mul_f32 v[2:3], v[2:3], s[12:13]
	v_cvt_pk_bf16_f32 v0, v0, v1
	v_cvt_pk_bf16_f32 v1, v2, v3
	ds_write_b64 v137, v[0:1] offset:24576
	s_branch .Lepi_lean_rows
; DEV u32x2 pk4(f32x4 v) { u32x2 r = {pk_bf16(v[0], v[1]), pk_bf16(v[2], v[3])}; return r; }
; DEV float fsigmoid(float x) { return 1.f / (1.f + __expf(-x)); }
;   DEV void operator()(f32x4 (&acc)[2][2][4][2], int brow, int bcol, int wr, int wc, int fr, int fq) const {
;     ...
;             } else if (mode == 2) {
;               for (int j = 0; j < 4; ++j) v[j] = fsigmoid(v[j]);
;               tile_put4(rl, cl, pk4(v));
.Lepi_lean_sigm:
	v_mul_f32_e32 v124, 0xbfb8aa3b, v124
	v_mul_f32_e32 v125, 0xbfb8aa3b, v125
	v_mul_f32_e32 v126, 0xbfb8aa3b, v126
	v_mul_f32_e32 v127, 0xbfb8aa3b, v127
	v_exp_f32_e32 v124, v124
	v_exp_f32_e32 v125, v125
	v_exp_f32_e32 v126, v126
	v_exp_f32_e32 v127, v127
	v_pk_add_f32 v[124:125], v[124:125], 1.0 op_sel_hi:[1,0]
	v_pk_add_f32 v[126:127], v[126:127], 1.0 op_sel_hi:[1,0]
	v_rcp_f32_e32 v124, v124
	v_rcp_f32_e32 v125, v125
	v_rcp_f32_e32 v126, v126
	v_rcp_f32_e32 v127, v127
	v_cvt_pk_bf16_f32 v124, v124, v125
	v_cvt_pk_bf16_f32 v125, v126, v127
	ds_write_b64 v134, v[124:125]
	v_mul_f32_e32 v120, 0xbfb8aa3b, v120
	v_mul_f32_e32 v121, 0xbfb8aa3b, v121
	v_mul_f32_e32 v122, 0xbfb8aa3b, v122
	v_mul_f32_e32 v123, 0xbfb8aa3b, v123
	v_exp_f32_e32 v120, v120
	v_exp_f32_e32 v121, v121
	v_exp_f32_e32 v122, v122
	v_exp_f32_e32 v123, v123
	v_pk_add_f32 v[120:121], v[120:121], 1.0 op_sel_hi:[1,0]
	v_pk_add_f32 v[122:123], v[122:123], 1.0 op_sel_hi:[1,0]
	v_rcp_f32_e32 v120, v120
	v_rcp_f32_e32 v121, v121
	v_rcp_f32_e32 v122, v122
	v_rcp_f32_e32 v123, v123
	v_cvt_pk_bf16_f32 v120, v120, v121
	v_cvt_pk_bf16_f32 v121, v122, v123
	ds_write_b64 v135, v[120:121]
	v_mul_f32_e32 v116, 0xbfb8aa3b, v116
	v_mul_f32_e32 v117, 0xbfb8aa3b, v117
	v_mul_f32_e32 v118, 0xbfb8aa3b, v118
	v_mul_f32_e32 v119, 0xbfb8aa3b, v119
	v_exp_f32_e32 v116, v116
	v_exp_f32_e32 v117, v117
	v_exp_f32_e32 v118, v118
	v_exp_f32_e32 v119, v119
	v_pk_add_f32 v[116:117], v[116:117], 1.0 op_sel_hi:[1,0]
	v_pk_add_f32 v[118:119], v[118:119], 1.0 op_sel_hi:[1,0]
	v_rcp_f32_e32 v116, v116
	v_rcp_f32_e32 v117, v117
	v_rcp_f32_e32 v118, v118
	v_rcp_f32_e32 v119, v119
	v_cvt_pk_bf16_f32 v116, v116, v117
	v_cvt_pk_bf16_f32 v117, v118, v119
	ds_write_b64 v134, v[116:117] offset:256
	v_mul_f32_e32 v112, 0xbfb8aa3b, v112
	v_mul_f32_e32 v113, 0xbfb8aa3b, v113
	v_mul_f32_e32 v114, 0xbfb8aa3b, v114
	v_mul_f32_e32 v115, 0xbfb8aa3b, v115
	v_exp_f32_e32 v112, v112
	v_exp_f32_e32 v113, v113
	v_exp_f32_e32 v114, v114
	v_exp_f32_e32 v115, v115
	v_pk_add_f32 v[112:113], v[112:113], 1.0 op_sel_hi:[1,0]
	v_pk_add_f32 v[114:115], v[114:115], 1.0 op_sel_hi:[1,0]
	v_rcp_f32_e32 v112, v112
	v_rcp_f32_e32 v113, v113
	v_rcp_f32_e32 v114, v114
	v_rcp_f32_e32 v115, v115
	v_cvt_pk_bf16_f32 v112, v112, v113
	v_cvt_pk_bf16_f32 v113, v114, v115
	ds_write_b64 v135, v[112:113] offset:256
	v_mul_f32_e32 v108, 0xbfb8aa3b, v108
	v_mul_f32_e32 v109, 0xbfb8aa3b, v109
	v_mul_f32_e32 v110, 0xbfb8aa3b, v110
	v_mul_f32_e32 v111, 0xbfb8aa3b, v111
	v_exp_f32_e32 v108, v108
	v_exp_f32_e32 v109, v109
	v_exp_f32_e32 v110, v110
	v_exp_f32_e32 v111, v111
	v_pk_add_f32 v[108:109], v[108:109], 1.0 op_sel_hi:[1,0]
	v_pk_add_f32 v[110:111], v[110:111], 1.0 op_sel_hi:[1,0]
	v_rcp_f32_e32 v108, v108
	v_rcp_f32_e32 v109, v109
	v_rcp_f32_e32 v110, v110
	v_rcp_f32_e32 v111, v111
	v_cvt_pk_bf16_f32 v108, v108, v109
	v_cvt_pk_bf16_f32 v109, v110, v111
	ds_write_b64 v134, v[108:109] offset:8448
	v_mul_f32_e32 v104, 0xbfb8aa3b, v104
	v_mul_f32_e32 v105, 0xbfb8aa3b, v105
	v_mul_f32_e32 v106, 0xbfb8aa3b, v106
	v_mul_f32_e32 v107, 0xbfb8aa3b, v107
	v_exp_f32_e32 v104, v104
	v_exp_f32_e32 v105, v105
	v_exp_f32_e32 v106, v106
	v_exp_f32_e32 v107, v107
	v_pk_add_f32 v[104:105], v[104:105], 1.0 op_sel_hi:[1,0]
	v_pk_add_f32 v[106:107], v[106:107], 1.0 op_sel_hi:[1,0]
	v_rcp_f32_e32 v104, v104
	v_rcp_f32_e32 v105, v105
	v_rcp_f32_e32 v106, v106
	v_rcp_f32_e32 v107, v107
	v_cvt_pk_bf16_f32 v104, v104, v105
	v_cvt_pk_bf16_f32 v105, v106, v107
	ds_write_b64 v135, v[104:105] offset:8448
	v_mul_f32_e32 v100, 0xbfb8aa3b, v100
	v_mul_f32_e32 v101, 0xbfb8aa3b, v101
	v_mul_f32_e32 v102, 0xbfb8aa3b, v102
	v_mul_f32_e32 v103, 0xbfb8aa3b, v103
	v_exp_f32_e32 v100, v100
	v_exp_f32_e32 v101, v101
	v_exp_f32_e32 v102, v102
	v_exp_f32_e32 v103, v103
	v_pk_add_f32 v[100:101], v[100:101], 1.0 op_sel_hi:[1,0]
	v_pk_add_f32 v[102:103], v[102:103], 1.0 op_sel_hi:[1,0]
	v_rcp_f32_e32 v100, v100
	v_rcp_f32_e32 v101, v101
	v_rcp_f32_e32 v102, v102
	v_rcp_f32_e32 v103, v103
	v_cvt_pk_bf16_f32 v100, v100, v101
	v_cvt_pk_bf16_f32 v101, v102, v103
	ds_write_b64 v134, v[100:101] offset:8192
	v_mul_f32_e32 v96, 0xbfb8aa3b, v96
	v_mul_f32_e32 v97, 0xbfb8aa3b, v97
	v_mul_f32_e32 v98, 0xbfb8aa3b, v98
	v_mul_f32_e32 v99, 0xbfb8aa3b, v99
	v_exp_f32_e32 v96, v96
	v_exp_f32_e32 v97, v97
	v_exp_f32_e32 v98, v98
	v_exp_f32_e32 v99, v99
	v_pk_add_f32 v[96:97], v[96:97], 1.0 op_sel_hi:[1,0]
	v_pk_add_f32 v[98:99], v[98:99], 1.0 op_sel_hi:[1,0]
	v_rcp_f32_e32 v96, v96
	v_rcp_f32_e32 v97, v97
	v_rcp_f32_e32 v98, v98
	v_rcp_f32_e32 v99, v99
	v_cvt_pk_bf16_f32 v96, v96, v97
	v_cvt_pk_bf16_f32 v97, v98, v99
	ds_write_b64 v135, v[96:97] offset:8192
	v_mul_f32_e32 v92, 0xbfb8aa3b, v92
	v_mul_f32_e32 v93, 0xbfb8aa3b, v93
	v_mul_f32_e32 v94, 0xbfb8aa3b, v94
	v_mul_f32_e32 v95, 0xbfb8aa3b, v95
	v_exp_f32_e32 v92, v92
	v_exp_f32_e32 v93, v93
	v_exp_f32_e32 v94, v94
	v_exp_f32_e32 v95, v95
	v_pk_add_f32 v[92:93], v[92:93], 1.0 op_sel_hi:[1,0]
	v_pk_add_f32 v[94:95], v[94:95], 1.0 op_sel_hi:[1,0]
	v_rcp_f32_e32 v92, v92
	v_rcp_f32_e32 v93, v93
	v_rcp_f32_e32 v94, v94
	v_rcp_f32_e32 v95, v95
	v_cvt_pk_bf16_f32 v92, v92, v93
	v_cvt_pk_bf16_f32 v93, v94, v95
	ds_write_b64 v134, v[92:93] offset:16384
	v_mul_f32_e32 v88, 0xbfb8aa3b, v88
	v_mul_f32_e32 v89, 0xbfb8aa3b, v89
	v_mul_f32_e32 v90, 0xbfb8aa3b, v90
	v_mul_f32_e32 v91, 0xbfb8aa3b, v91
	v_exp_f32_e32 v88, v88
	v_exp_f32_e32 v89, v89
	v_exp_f32_e32 v90, v90
	v_exp_f32_e32 v91, v91
	v_pk_add_f32 v[88:89], v[88:89], 1.0 op_sel_hi:[1,0]
	v_pk_add_f32 v[90:91], v[90:91], 1.0 op_sel_hi:[1,0]
	v_rcp_f32_e32 v88, v88
	v_rcp_f32_e32 v89, v89
	v_rcp_f32_e32 v90, v90
; DEV u32x2 pk4(f32x4 v) { u32x2 r = {pk_bf16(v[0], v[1]), pk_bf16(v[2], v[3])}; return r; }
; DEV float fsigmoid(float x) { return 1.f / (1.f + __expf(-x)); }
;   DEV void operator()(f32x4 (&acc)[2][2][4][2], int brow, int bcol, int wr, int wc, int fr, int fq) const {
;     ...
;     for (int ai = 0; ai < 2; ++ai)
; #pragma unroll
;       for (int m = 0; m < 4; ++m) {
;         const int rl = ai * 128 + wr * 64 + m * 16 + fr, tok = brow + rl;
; #pragma unroll
;         for (int bj = 0; bj < 2; ++bj)
; #pragma unroll
;           for (int n = 0; n < 2; ++n) {
;             const int cl = bj * 128 + wc * 32 + n * 16 + fq * 4, lc = bcol - segstart + cl;
;             f32x4 v = acc[ai][bj][m][n];
;             if (mode == 0) {
;               tile_put4(rl, cl, pk4(v * scale));
;             } else if (mode == 1) {
;               for (int j = 0; j < 4; ++j) v[j] = v[j] * fsigmoid(v[j]);
;               tile_put4(rl, cl, pk4(v));
;             } else if (mode == 2) {
;               for (int j = 0; j < 4; ++j) v[j] = fsigmoid(v[j]);
;               tile_put4(rl, cl, pk4(v));
	v_rcp_f32_e32 v91, v91
	v_cvt_pk_bf16_f32 v88, v88, v89
	v_cvt_pk_bf16_f32 v89, v90, v91
	ds_write_b64 v135, v[88:89] offset:16384
	v_mul_f32_e32 v84, 0xbfb8aa3b, v84
	v_mul_f32_e32 v85, 0xbfb8aa3b, v85
	v_mul_f32_e32 v86, 0xbfb8aa3b, v86
	v_mul_f32_e32 v87, 0xbfb8aa3b, v87
	v_exp_f32_e32 v84, v84
	v_exp_f32_e32 v85, v85
	v_exp_f32_e32 v86, v86
	v_exp_f32_e32 v87, v87
	v_pk_add_f32 v[84:85], v[84:85], 1.0 op_sel_hi:[1,0]
	v_pk_add_f32 v[86:87], v[86:87], 1.0 op_sel_hi:[1,0]
	v_rcp_f32_e32 v84, v84
	v_rcp_f32_e32 v85, v85
	v_rcp_f32_e32 v86, v86
	v_rcp_f32_e32 v87, v87
	v_cvt_pk_bf16_f32 v84, v84, v85
	v_cvt_pk_bf16_f32 v85, v86, v87
	ds_write_b64 v134, v[84:85] offset:16640
	v_mul_f32_e32 v80, 0xbfb8aa3b, v80
	v_mul_f32_e32 v81, 0xbfb8aa3b, v81
	v_mul_f32_e32 v82, 0xbfb8aa3b, v82
	v_mul_f32_e32 v83, 0xbfb8aa3b, v83
	v_exp_f32_e32 v80, v80
	v_exp_f32_e32 v81, v81
	v_exp_f32_e32 v82, v82
	v_exp_f32_e32 v83, v83
	v_pk_add_f32 v[80:81], v[80:81], 1.0 op_sel_hi:[1,0]
	v_pk_add_f32 v[82:83], v[82:83], 1.0 op_sel_hi:[1,0]
	v_rcp_f32_e32 v80, v80
	v_rcp_f32_e32 v81, v81
	v_rcp_f32_e32 v82, v82
	v_rcp_f32_e32 v83, v83
	v_cvt_pk_bf16_f32 v80, v80, v81
	v_cvt_pk_bf16_f32 v81, v82, v83
	ds_write_b64 v135, v[80:81] offset:16640
	v_mul_f32_e32 v76, 0xbfb8aa3b, v76
	v_mul_f32_e32 v77, 0xbfb8aa3b, v77
	v_mul_f32_e32 v78, 0xbfb8aa3b, v78
	v_mul_f32_e32 v79, 0xbfb8aa3b, v79
	v_exp_f32_e32 v76, v76
	v_exp_f32_e32 v77, v77
	v_exp_f32_e32 v78, v78
	v_exp_f32_e32 v79, v79
	v_pk_add_f32 v[76:77], v[76:77], 1.0 op_sel_hi:[1,0]
	v_pk_add_f32 v[78:79], v[78:79], 1.0 op_sel_hi:[1,0]
	v_rcp_f32_e32 v76, v76
	v_rcp_f32_e32 v77, v77
	v_rcp_f32_e32 v78, v78
	v_rcp_f32_e32 v79, v79
	v_cvt_pk_bf16_f32 v76, v76, v77
	v_cvt_pk_bf16_f32 v77, v78, v79
	ds_write_b64 v134, v[76:77] offset:24832
	v_mul_f32_e32 v72, 0xbfb8aa3b, v72
	v_mul_f32_e32 v73, 0xbfb8aa3b, v73
	v_mul_f32_e32 v74, 0xbfb8aa3b, v74
	v_mul_f32_e32 v75, 0xbfb8aa3b, v75
	v_exp_f32_e32 v72, v72
	v_exp_f32_e32 v73, v73
	v_exp_f32_e32 v74, v74
	v_exp_f32_e32 v75, v75
	v_pk_add_f32 v[72:73], v[72:73], 1.0 op_sel_hi:[1,0]
	v_pk_add_f32 v[74:75], v[74:75], 1.0 op_sel_hi:[1,0]
	v_rcp_f32_e32 v72, v72
	v_rcp_f32_e32 v73, v73
	v_rcp_f32_e32 v74, v74
	v_rcp_f32_e32 v75, v75
	v_cvt_pk_bf16_f32 v72, v72, v73
	v_cvt_pk_bf16_f32 v73, v74, v75
	ds_write_b64 v135, v[72:73] offset:24832
	v_mul_f32_e32 v68, 0xbfb8aa3b, v68
	v_mul_f32_e32 v69, 0xbfb8aa3b, v69
	v_mul_f32_e32 v70, 0xbfb8aa3b, v70
	v_mul_f32_e32 v71, 0xbfb8aa3b, v71
	v_exp_f32_e32 v68, v68
	v_exp_f32_e32 v69, v69
	v_exp_f32_e32 v70, v70
	v_exp_f32_e32 v71, v71
	v_pk_add_f32 v[68:69], v[68:69], 1.0 op_sel_hi:[1,0]
	v_pk_add_f32 v[70:71], v[70:71], 1.0 op_sel_hi:[1,0]
	v_rcp_f32_e32 v68, v68
	v_rcp_f32_e32 v69, v69
	v_rcp_f32_e32 v70, v70
	v_rcp_f32_e32 v71, v71
	v_cvt_pk_bf16_f32 v68, v68, v69
	v_cvt_pk_bf16_f32 v69, v70, v71
	ds_write_b64 v134, v[68:69] offset:24576
	v_mul_f32_e32 v64, 0xbfb8aa3b, v64
	v_mul_f32_e32 v65, 0xbfb8aa3b, v65
	v_mul_f32_e32 v66, 0xbfb8aa3b, v66
	v_mul_f32_e32 v67, 0xbfb8aa3b, v67
	v_exp_f32_e32 v64, v64
	v_exp_f32_e32 v65, v65
	v_exp_f32_e32 v66, v66
	v_exp_f32_e32 v67, v67
	v_pk_add_f32 v[64:65], v[64:65], 1.0 op_sel_hi:[1,0]
	v_pk_add_f32 v[66:67], v[66:67], 1.0 op_sel_hi:[1,0]
	v_rcp_f32_e32 v64, v64
	v_rcp_f32_e32 v65, v65
	v_rcp_f32_e32 v66, v66
	v_rcp_f32_e32 v67, v67
	v_cvt_pk_bf16_f32 v64, v64, v65
	v_cvt_pk_bf16_f32 v65, v66, v67
	ds_write_b64 v135, v[64:65] offset:24576
	v_mul_f32_e32 v60, 0xbfb8aa3b, v60
	v_mul_f32_e32 v61, 0xbfb8aa3b, v61
	v_mul_f32_e32 v62, 0xbfb8aa3b, v62
	v_mul_f32_e32 v63, 0xbfb8aa3b, v63
	v_exp_f32_e32 v60, v60
	v_exp_f32_e32 v61, v61
	v_exp_f32_e32 v62, v62
	v_exp_f32_e32 v63, v63
	v_pk_add_f32 v[60:61], v[60:61], 1.0 op_sel_hi:[1,0]
	v_pk_add_f32 v[62:63], v[62:63], 1.0 op_sel_hi:[1,0]
	v_rcp_f32_e32 v60, v60
	v_rcp_f32_e32 v61, v61
	v_rcp_f32_e32 v62, v62
	v_rcp_f32_e32 v63, v63
	v_cvt_pk_bf16_f32 v60, v60, v61
	v_cvt_pk_bf16_f32 v61, v62, v63
	ds_write_b64 v136, v[60:61]
	v_mul_f32_e32 v56, 0xbfb8aa3b, v56
	v_mul_f32_e32 v57, 0xbfb8aa3b, v57
	v_mul_f32_e32 v58, 0xbfb8aa3b, v58
	v_mul_f32_e32 v59, 0xbfb8aa3b, v59
	v_exp_f32_e32 v56, v56
	v_exp_f32_e32 v57, v57
	v_exp_f32_e32 v58, v58
	v_exp_f32_e32 v59, v59
	v_pk_add_f32 v[56:57], v[56:57], 1.0 op_sel_hi:[1,0]
	v_pk_add_f32 v[58:59], v[58:59], 1.0 op_sel_hi:[1,0]
	v_rcp_f32_e32 v56, v56
	v_rcp_f32_e32 v57, v57
	v_rcp_f32_e32 v58, v58
	v_rcp_f32_e32 v59, v59
	v_cvt_pk_bf16_f32 v56, v56, v57
	v_cvt_pk_bf16_f32 v57, v58, v59
	ds_write_b64 v137, v[56:57]
	v_mul_f32_e32 v52, 0xbfb8aa3b, v52
	v_mul_f32_e32 v53, 0xbfb8aa3b, v53
	v_mul_f32_e32 v54, 0xbfb8aa3b, v54
	v_mul_f32_e32 v55, 0xbfb8aa3b, v55
	v_exp_f32_e32 v52, v52
	v_exp_f32_e32 v53, v53
	v_exp_f32_e32 v54, v54
	v_exp_f32_e32 v55, v55
	v_pk_add_f32 v[52:53], v[52:53], 1.0 op_sel_hi:[1,0]
	v_pk_add_f32 v[54:55], v[54:55], 1.0 op_sel_hi:[1,0]
	v_rcp_f32_e32 v52, v52
	v_rcp_f32_e32 v53, v53
	v_rcp_f32_e32 v54, v54
	v_rcp_f32_e32 v55, v55
	v_cvt_pk_bf16_f32 v52, v52, v53
	v_cvt_pk_bf16_f32 v53, v54, v55
	ds_write_b64 v136, v[52:53] offset:256
	v_mul_f32_e32 v48, 0xbfb8aa3b, v48
	v_mul_f32_e32 v49, 0xbfb8aa3b, v49
	v_mul_f32_e32 v50, 0xbfb8aa3b, v50
	v_mul_f32_e32 v51, 0xbfb8aa3b, v51
	v_exp_f32_e32 v48, v48
	v_exp_f32_e32 v49, v49
	v_exp_f32_e32 v50, v50
	v_exp_f32_e32 v51, v51
	v_pk_add_f32 v[48:49], v[48:49], 1.0 op_sel_hi:[1,0]
	v_pk_add_f32 v[50:51], v[50:51], 1.0 op_sel_hi:[1,0]
	v_rcp_f32_e32 v48, v48
	v_rcp_f32_e32 v49, v49
	v_rcp_f32_e32 v50, v50
	v_rcp_f32_e32 v51, v51
	v_cvt_pk_bf16_f32 v48, v48, v49
	v_cvt_pk_bf16_f32 v49, v50, v51
	ds_write_b64 v137, v[48:49] offset:256
; DEV u32x2 pk4(f32x4 v) { u32x2 r = {pk_bf16(v[0], v[1]), pk_bf16(v[2], v[3])}; return r; }
; DEV float fsigmoid(float x) { return 1.f / (1.f + __expf(-x)); }
;   DEV void operator()(f32x4 (&acc)[2][2][4][2], int brow, int bcol, int wr, int wc, int fr, int fq) const {
;     ...
;     for (int ai = 0; ai < 2; ++ai)
; #pragma unroll
;       for (int m = 0; m < 4; ++m) {
;         const int rl = ai * 128 + wr * 64 + m * 16 + fr, tok = brow + rl;
; #pragma unroll
;         for (int bj = 0; bj < 2; ++bj)
; #pragma unroll
;           for (int n = 0; n < 2; ++n) {
;             const int cl = bj * 128 + wc * 32 + n * 16 + fq * 4, lc = bcol - segstart + cl;
;             f32x4 v = acc[ai][bj][m][n];
;             if (mode == 0) {
;               tile_put4(rl, cl, pk4(v * scale));
;             } else if (mode == 1) {
;               for (int j = 0; j < 4; ++j) v[j] = v[j] * fsigmoid(v[j]);
;               tile_put4(rl, cl, pk4(v));
;             } else if (mode == 2) {
;               for (int j = 0; j < 4; ++j) v[j] = fsigmoid(v[j]);
;               tile_put4(rl, cl, pk4(v));
	v_mul_f32_e32 v44, 0xbfb8aa3b, v44
	v_mul_f32_e32 v45, 0xbfb8aa3b, v45
	v_mul_f32_e32 v46, 0xbfb8aa3b, v46
	v_mul_f32_e32 v47, 0xbfb8aa3b, v47
	v_exp_f32_e32 v44, v44
	v_exp_f32_e32 v45, v45
	v_exp_f32_e32 v46, v46
	v_exp_f32_e32 v47, v47
	v_pk_add_f32 v[44:45], v[44:45], 1.0 op_sel_hi:[1,0]
	v_pk_add_f32 v[46:47], v[46:47], 1.0 op_sel_hi:[1,0]
	v_rcp_f32_e32 v44, v44
	v_rcp_f32_e32 v45, v45
	v_rcp_f32_e32 v46, v46
	v_rcp_f32_e32 v47, v47
	v_cvt_pk_bf16_f32 v44, v44, v45
	v_cvt_pk_bf16_f32 v45, v46, v47
	ds_write_b64 v136, v[44:45] offset:8448
	v_mul_f32_e32 v40, 0xbfb8aa3b, v40
	v_mul_f32_e32 v41, 0xbfb8aa3b, v41
	v_mul_f32_e32 v42, 0xbfb8aa3b, v42
	v_mul_f32_e32 v43, 0xbfb8aa3b, v43
	v_exp_f32_e32 v40, v40
	v_exp_f32_e32 v41, v41
	v_exp_f32_e32 v42, v42
	v_exp_f32_e32 v43, v43
	v_pk_add_f32 v[40:41], v[40:41], 1.0 op_sel_hi:[1,0]
	v_pk_add_f32 v[42:43], v[42:43], 1.0 op_sel_hi:[1,0]
	v_rcp_f32_e32 v40, v40
	v_rcp_f32_e32 v41, v41
	v_rcp_f32_e32 v42, v42
	v_rcp_f32_e32 v43, v43
	v_cvt_pk_bf16_f32 v40, v40, v41
	v_cvt_pk_bf16_f32 v41, v42, v43
	ds_write_b64 v137, v[40:41] offset:8448
	v_mul_f32_e32 v36, 0xbfb8aa3b, v36
	v_mul_f32_e32 v37, 0xbfb8aa3b, v37
	v_mul_f32_e32 v38, 0xbfb8aa3b, v38
	v_mul_f32_e32 v39, 0xbfb8aa3b, v39
	v_exp_f32_e32 v36, v36
	v_exp_f32_e32 v37, v37
	v_exp_f32_e32 v38, v38
	v_exp_f32_e32 v39, v39
	v_pk_add_f32 v[36:37], v[36:37], 1.0 op_sel_hi:[1,0]
	v_pk_add_f32 v[38:39], v[38:39], 1.0 op_sel_hi:[1,0]
	v_rcp_f32_e32 v36, v36
	v_rcp_f32_e32 v37, v37
	v_rcp_f32_e32 v38, v38
	v_rcp_f32_e32 v39, v39
	v_cvt_pk_bf16_f32 v36, v36, v37
	v_cvt_pk_bf16_f32 v37, v38, v39
	ds_write_b64 v136, v[36:37] offset:8192
	v_mul_f32_e32 v32, 0xbfb8aa3b, v32
	v_mul_f32_e32 v33, 0xbfb8aa3b, v33
	v_mul_f32_e32 v34, 0xbfb8aa3b, v34
	v_mul_f32_e32 v35, 0xbfb8aa3b, v35
	v_exp_f32_e32 v32, v32
	v_exp_f32_e32 v33, v33
	v_exp_f32_e32 v34, v34
	v_exp_f32_e32 v35, v35
	v_pk_add_f32 v[32:33], v[32:33], 1.0 op_sel_hi:[1,0]
	v_pk_add_f32 v[34:35], v[34:35], 1.0 op_sel_hi:[1,0]
	v_rcp_f32_e32 v32, v32
	v_rcp_f32_e32 v33, v33
	v_rcp_f32_e32 v34, v34
	v_rcp_f32_e32 v35, v35
	v_cvt_pk_bf16_f32 v32, v32, v33
	v_cvt_pk_bf16_f32 v33, v34, v35
	ds_write_b64 v137, v[32:33] offset:8192
	v_mul_f32_e32 v28, 0xbfb8aa3b, v28
	v_mul_f32_e32 v29, 0xbfb8aa3b, v29
	v_mul_f32_e32 v30, 0xbfb8aa3b, v30
	v_mul_f32_e32 v31, 0xbfb8aa3b, v31
	v_exp_f32_e32 v28, v28
	v_exp_f32_e32 v29, v29
	v_exp_f32_e32 v30, v30
	v_exp_f32_e32 v31, v31
	v_pk_add_f32 v[28:29], v[28:29], 1.0 op_sel_hi:[1,0]
	v_pk_add_f32 v[30:31], v[30:31], 1.0 op_sel_hi:[1,0]
	v_rcp_f32_e32 v28, v28
	v_rcp_f32_e32 v29, v29
	v_rcp_f32_e32 v30, v30
	v_rcp_f32_e32 v31, v31
	v_cvt_pk_bf16_f32 v28, v28, v29
	v_cvt_pk_bf16_f32 v29, v30, v31
	ds_write_b64 v136, v[28:29] offset:16384
	v_mul_f32_e32 v24, 0xbfb8aa3b, v24
	v_mul_f32_e32 v25, 0xbfb8aa3b, v25
	v_mul_f32_e32 v26, 0xbfb8aa3b, v26
	v_mul_f32_e32 v27, 0xbfb8aa3b, v27
	v_exp_f32_e32 v24, v24
	v_exp_f32_e32 v25, v25
	v_exp_f32_e32 v26, v26
	v_exp_f32_e32 v27, v27
	v_pk_add_f32 v[24:25], v[24:25], 1.0 op_sel_hi:[1,0]
	v_pk_add_f32 v[26:27], v[26:27], 1.0 op_sel_hi:[1,0]
	v_rcp_f32_e32 v24, v24
	v_rcp_f32_e32 v25, v25
	v_rcp_f32_e32 v26, v26
	v_rcp_f32_e32 v27, v27
	v_cvt_pk_bf16_f32 v24, v24, v25
	v_cvt_pk_bf16_f32 v25, v26, v27
	ds_write_b64 v137, v[24:25] offset:16384
	v_mul_f32_e32 v20, 0xbfb8aa3b, v20
	v_mul_f32_e32 v21, 0xbfb8aa3b, v21
	v_mul_f32_e32 v22, 0xbfb8aa3b, v22
	v_mul_f32_e32 v23, 0xbfb8aa3b, v23
	v_exp_f32_e32 v20, v20
	v_exp_f32_e32 v21, v21
	v_exp_f32_e32 v22, v22
	v_exp_f32_e32 v23, v23
	v_pk_add_f32 v[20:21], v[20:21], 1.0 op_sel_hi:[1,0]
	v_pk_add_f32 v[22:23], v[22:23], 1.0 op_sel_hi:[1,0]
	v_rcp_f32_e32 v20, v20
	v_rcp_f32_e32 v21, v21
	v_rcp_f32_e32 v22, v22
	v_rcp_f32_e32 v23, v23
	v_cvt_pk_bf16_f32 v20, v20, v21
	v_cvt_pk_bf16_f32 v21, v22, v23
	ds_write_b64 v136, v[20:21] offset:16640
	v_mul_f32_e32 v16, 0xbfb8aa3b, v16
	v_mul_f32_e32 v17, 0xbfb8aa3b, v17
	v_mul_f32_e32 v18, 0xbfb8aa3b, v18
	v_mul_f32_e32 v19, 0xbfb8aa3b, v19
	v_exp_f32_e32 v16, v16
	v_exp_f32_e32 v17, v17
	v_exp_f32_e32 v18, v18
	v_exp_f32_e32 v19, v19
	v_pk_add_f32 v[16:17], v[16:17], 1.0 op_sel_hi:[1,0]
	v_pk_add_f32 v[18:19], v[18:19], 1.0 op_sel_hi:[1,0]
	v_rcp_f32_e32 v16, v16
	v_rcp_f32_e32 v17, v17
	v_rcp_f32_e32 v18, v18
	v_rcp_f32_e32 v19, v19
	v_cvt_pk_bf16_f32 v16, v16, v17
	v_cvt_pk_bf16_f32 v17, v18, v19
	ds_write_b64 v137, v[16:17] offset:16640
	v_mul_f32_e32 v12, 0xbfb8aa3b, v12
	v_mul_f32_e32 v13, 0xbfb8aa3b, v13
	v_mul_f32_e32 v14, 0xbfb8aa3b, v14
	v_mul_f32_e32 v15, 0xbfb8aa3b, v15
	v_exp_f32_e32 v12, v12
	v_exp_f32_e32 v13, v13
	v_exp_f32_e32 v14, v14
	v_exp_f32_e32 v15, v15
	v_pk_add_f32 v[12:13], v[12:13], 1.0 op_sel_hi:[1,0]
	v_pk_add_f32 v[14:15], v[14:15], 1.0 op_sel_hi:[1,0]
	v_rcp_f32_e32 v12, v12
	v_rcp_f32_e32 v13, v13
	v_rcp_f32_e32 v14, v14
	v_rcp_f32_e32 v15, v15
	v_cvt_pk_bf16_f32 v12, v12, v13
	v_cvt_pk_bf16_f32 v13, v14, v15
	ds_write_b64 v136, v[12:13] offset:24832
	v_mul_f32_e32 v8, 0xbfb8aa3b, v8
	v_mul_f32_e32 v9, 0xbfb8aa3b, v9
	v_mul_f32_e32 v10, 0xbfb8aa3b, v10
	v_mul_f32_e32 v11, 0xbfb8aa3b, v11
	v_exp_f32_e32 v8, v8
	v_exp_f32_e32 v9, v9
	v_exp_f32_e32 v10, v10
	v_exp_f32_e32 v11, v11
	v_pk_add_f32 v[8:9], v[8:9], 1.0 op_sel_hi:[1,0]
	v_pk_add_f32 v[10:11], v[10:11], 1.0 op_sel_hi:[1,0]
	v_rcp_f32_e32 v8, v8
	v_rcp_f32_e32 v9, v9
	v_rcp_f32_e32 v10, v10
	v_rcp_f32_e32 v11, v11
	v_cvt_pk_bf16_f32 v8, v8, v9
	v_cvt_pk_bf16_f32 v9, v10, v11
	ds_write_b64 v137, v[8:9] offset:24832
	v_mul_f32_e32 v4, 0xbfb8aa3b, v4
	v_mul_f32_e32 v5, 0xbfb8aa3b, v5
	v_mul_f32_e32 v6, 0xbfb8aa3b, v6
	v_mul_f32_e32 v7, 0xbfb8aa3b, v7
	v_exp_f32_e32 v4, v4
	v_exp_f32_e32 v5, v5
	v_exp_f32_e32 v6, v6
	v_exp_f32_e32 v7, v7
	v_pk_add_f32 v[4:5], v[4:5], 1.0 op_sel_hi:[1,0]
	v_pk_add_f32 v[6:7], v[6:7], 1.0 op_sel_hi:[1,0]
	v_rcp_f32_e32 v4, v4
	v_rcp_f32_e32 v5, v5
	v_rcp_f32_e32 v6, v6
	v_rcp_f32_e32 v7, v7
	v_cvt_pk_bf16_f32 v4, v4, v5
	v_cvt_pk_bf16_f32 v5, v6, v7
	ds_write_b64 v136, v[4:5] offset:24576
	v_mul_f32_e32 v0, 0xbfb8aa3b, v0
	v_mul_f32_e32 v1, 0xbfb8aa3b, v1
	v_mul_f32_e32 v2, 0xbfb8aa3b, v2
	v_mul_f32_e32 v3, 0xbfb8aa3b, v3
	v_exp_f32_e32 v0, v0
	v_exp_f32_e32 v1, v1
	v_exp_f32_e32 v2, v2
	v_exp_f32_e32 v3, v3
	v_pk_add_f32 v[0:1], v[0:1], 1.0 op_sel_hi:[1,0]
	v_pk_add_f32 v[2:3], v[2:3], 1.0 op_sel_hi:[1,0]
	v_rcp_f32_e32 v0, v0
	v_rcp_f32_e32 v1, v1
	v_rcp_f32_e32 v2, v2
	v_rcp_f32_e32 v3, v3
	v_cvt_pk_bf16_f32 v0, v0, v1
	v_cvt_pk_bf16_f32 v1, v2, v3
	ds_write_b64 v137, v[0:1] offset:24576
	s_branch .Lepi_lean_rows
; DEV u32x2 pk4(f32x4 v) { u32x2 r = {pk_bf16(v[0], v[1]), pk_bf16(v[2], v[3])}; return r; }
; DEV float fsigmoid(float x) { return 1.f / (1.f + __expf(-x)); }
;   DEV void operator()(f32x4 (&acc)[2][2][4][2], int brow, int bcol, int wr, int wc, int fr, int fq) const {
;     ...
;     for (int ai = 0; ai < 2; ++ai)
; #pragma unroll
;       for (int m = 0; m < 4; ++m) {
;         const int rl = ai * 128 + wr * 64 + m * 16 + fr, tok = brow + rl;
; #pragma unroll
;         for (int bj = 0; bj < 2; ++bj)
; #pragma unroll
;           for (int n = 0; n < 2; ++n) {
;             const int cl = bj * 128 + wc * 32 + n * 16 + fq * 4, lc = bcol - segstart + cl;
;             f32x4 v = acc[ai][bj][m][n];
;             if (mode == 0) {
;               tile_put4(rl, cl, pk4(v * scale));
;             } else if (mode == 1) {
;               for (int j = 0; j < 4; ++j) v[j] = v[j] * fsigmoid(v[j]);
;               tile_put4(rl, cl, pk4(v));
.Lepi_lean_silu:
	v_mul_f32_e32 v140, 0xbfb8aa3b, v124
	v_mul_f32_e32 v141, 0xbfb8aa3b, v125
	v_mul_f32_e32 v142, 0xbfb8aa3b, v126
	v_mul_f32_e32 v143, 0xbfb8aa3b, v127
	v_exp_f32_e32 v140, v140
	v_exp_f32_e32 v141, v141
	v_exp_f32_e32 v142, v142
	v_exp_f32_e32 v143, v143
	v_pk_add_f32 v[140:141], v[140:141], 1.0 op_sel_hi:[1,0]
	v_pk_add_f32 v[142:143], v[142:143], 1.0 op_sel_hi:[1,0]
	v_rcp_f32_e32 v140, v140
	v_rcp_f32_e32 v141, v141
	v_rcp_f32_e32 v142, v142
	v_rcp_f32_e32 v143, v143
	v_pk_mul_f32 v[124:125], v[124:125], v[140:141]
	v_pk_mul_f32 v[126:127], v[126:127], v[142:143]
	v_cvt_pk_bf16_f32 v124, v124, v125
	v_cvt_pk_bf16_f32 v125, v126, v127
	ds_write_b64 v134, v[124:125]
	v_mul_f32_e32 v144, 0xbfb8aa3b, v120
	v_mul_f32_e32 v145, 0xbfb8aa3b, v121
	v_mul_f32_e32 v146, 0xbfb8aa3b, v122
	v_mul_f32_e32 v147, 0xbfb8aa3b, v123
	v_exp_f32_e32 v144, v144
	v_exp_f32_e32 v145, v145
	v_exp_f32_e32 v146, v146
	v_exp_f32_e32 v147, v147
	v_pk_add_f32 v[144:145], v[144:145], 1.0 op_sel_hi:[1,0]
	v_pk_add_f32 v[146:147], v[146:147], 1.0 op_sel_hi:[1,0]
	v_rcp_f32_e32 v144, v144
	v_rcp_f32_e32 v145, v145
	v_rcp_f32_e32 v146, v146
	v_rcp_f32_e32 v147, v147
	v_pk_mul_f32 v[120:121], v[120:121], v[144:145]
	v_pk_mul_f32 v[122:123], v[122:123], v[146:147]
	v_cvt_pk_bf16_f32 v120, v120, v121
	v_cvt_pk_bf16_f32 v121, v122, v123
	ds_write_b64 v135, v[120:121]
	v_mul_f32_e32 v140, 0xbfb8aa3b, v116
	v_mul_f32_e32 v141, 0xbfb8aa3b, v117
	v_mul_f32_e32 v142, 0xbfb8aa3b, v118
	v_mul_f32_e32 v143, 0xbfb8aa3b, v119
	v_exp_f32_e32 v140, v140
	v_exp_f32_e32 v141, v141
	v_exp_f32_e32 v142, v142
	v_exp_f32_e32 v143, v143
	v_pk_add_f32 v[140:141], v[140:141], 1.0 op_sel_hi:[1,0]
	v_pk_add_f32 v[142:143], v[142:143], 1.0 op_sel_hi:[1,0]
	v_rcp_f32_e32 v140, v140
	v_rcp_f32_e32 v141, v141
	v_rcp_f32_e32 v142, v142
	v_rcp_f32_e32 v143, v143
	v_pk_mul_f32 v[116:117], v[116:117], v[140:141]
	v_pk_mul_f32 v[118:119], v[118:119], v[142:143]
	v_cvt_pk_bf16_f32 v116, v116, v117
	v_cvt_pk_bf16_f32 v117, v118, v119
	ds_write_b64 v134, v[116:117] offset:256
	v_mul_f32_e32 v144, 0xbfb8aa3b, v112
	v_mul_f32_e32 v145, 0xbfb8aa3b, v113
	v_mul_f32_e32 v146, 0xbfb8aa3b, v114
	v_mul_f32_e32 v147, 0xbfb8aa3b, v115
	v_exp_f32_e32 v144, v144
	v_exp_f32_e32 v145, v145
	v_exp_f32_e32 v146, v146
	v_exp_f32_e32 v147, v147
	v_pk_add_f32 v[144:145], v[144:145], 1.0 op_sel_hi:[1,0]
	v_pk_add_f32 v[146:147], v[146:147], 1.0 op_sel_hi:[1,0]
	v_rcp_f32_e32 v144, v144
	v_rcp_f32_e32 v145, v145
	v_rcp_f32_e32 v146, v146
	v_rcp_f32_e32 v147, v147
	v_pk_mul_f32 v[112:113], v[112:113], v[144:145]
	v_pk_mul_f32 v[114:115], v[114:115], v[146:147]
	v_cvt_pk_bf16_f32 v112, v112, v113
	v_cvt_pk_bf16_f32 v113, v114, v115
	ds_write_b64 v135, v[112:113] offset:256
	v_mul_f32_e32 v140, 0xbfb8aa3b, v108
	v_mul_f32_e32 v141, 0xbfb8aa3b, v109
	v_mul_f32_e32 v142, 0xbfb8aa3b, v110
	v_mul_f32_e32 v143, 0xbfb8aa3b, v111
	v_exp_f32_e32 v140, v140
	v_exp_f32_e32 v141, v141
	v_exp_f32_e32 v142, v142
	v_exp_f32_e32 v143, v143
	v_pk_add_f32 v[140:141], v[140:141], 1.0 op_sel_hi:[1,0]
	v_pk_add_f32 v[142:143], v[142:143], 1.0 op_sel_hi:[1,0]
	v_rcp_f32_e32 v140, v140
	v_rcp_f32_e32 v141, v141
	v_rcp_f32_e32 v142, v142
	v_rcp_f32_e32 v143, v143
	v_pk_mul_f32 v[108:109], v[108:109], v[140:141]
	v_pk_mul_f32 v[110:111], v[110:111], v[142:143]
	v_cvt_pk_bf16_f32 v108, v108, v109
	v_cvt_pk_bf16_f32 v109, v110, v111
	ds_write_b64 v134, v[108:109] offset:8448
	v_mul_f32_e32 v144, 0xbfb8aa3b, v104
	v_mul_f32_e32 v145, 0xbfb8aa3b, v105
	v_mul_f32_e32 v146, 0xbfb8aa3b, v106
	v_mul_f32_e32 v147, 0xbfb8aa3b, v107
	v_exp_f32_e32 v144, v144
	v_exp_f32_e32 v145, v145
	v_exp_f32_e32 v146, v146
	v_exp_f32_e32 v147, v147
	v_pk_add_f32 v[144:145], v[144:145], 1.0 op_sel_hi:[1,0]
	v_pk_add_f32 v[146:147], v[146:147], 1.0 op_sel_hi:[1,0]
	v_rcp_f32_e32 v144, v144
	v_rcp_f32_e32 v145, v145
	v_rcp_f32_e32 v146, v146
	v_rcp_f32_e32 v147, v147
	v_pk_mul_f32 v[104:105], v[104:105], v[144:145]
	v_pk_mul_f32 v[106:107], v[106:107], v[146:147]
	v_cvt_pk_bf16_f32 v104, v104, v105
	v_cvt_pk_bf16_f32 v105, v106, v107
	ds_write_b64 v135, v[104:105] offset:8448
	v_mul_f32_e32 v140, 0xbfb8aa3b, v100
	v_mul_f32_e32 v141, 0xbfb8aa3b, v101
	v_mul_f32_e32 v142, 0xbfb8aa3b, v102
	v_mul_f32_e32 v143, 0xbfb8aa3b, v103
	v_exp_f32_e32 v140, v140
	v_exp_f32_e32 v141, v141
	v_exp_f32_e32 v142, v142
	v_exp_f32_e32 v143, v143
	v_pk_add_f32 v[140:141], v[140:141], 1.0 op_sel_hi:[1,0]
	v_pk_add_f32 v[142:143], v[142:143], 1.0 op_sel_hi:[1,0]
	v_rcp_f32_e32 v140, v140
	v_rcp_f32_e32 v141, v141
	v_rcp_f32_e32 v142, v142
	v_rcp_f32_e32 v143, v143
	v_pk_mul_f32 v[100:101], v[100:101], v[140:141]
	v_pk_mul_f32 v[102:103], v[102:103], v[142:143]
	v_cvt_pk_bf16_f32 v100, v100, v101
	v_cvt_pk_bf16_f32 v101, v102, v103
	ds_write_b64 v134, v[100:101] offset:8192
	v_mul_f32_e32 v144, 0xbfb8aa3b, v96
	v_mul_f32_e32 v145, 0xbfb8aa3b, v97
	v_mul_f32_e32 v146, 0xbfb8aa3b, v98
	v_mul_f32_e32 v147, 0xbfb8aa3b, v99
	v_exp_f32_e32 v144, v144
	v_exp_f32_e32 v145, v145
	v_exp_f32_e32 v146, v146
	v_exp_f32_e32 v147, v147
	v_pk_add_f32 v[144:145], v[144:145], 1.0 op_sel_hi:[1,0]
	v_pk_add_f32 v[146:147], v[146:147], 1.0 op_sel_hi:[1,0]
	v_rcp_f32_e32 v144, v144
	v_rcp_f32_e32 v145, v145
	v_rcp_f32_e32 v146, v146
	v_rcp_f32_e32 v147, v147
	v_pk_mul_f32 v[96:97], v[96:97], v[144:145]
	v_pk_mul_f32 v[98:99], v[98:99], v[146:147]
	v_cvt_pk_bf16_f32 v96, v96, v97
	v_cvt_pk_bf16_f32 v97, v98, v99
	ds_write_b64 v135, v[96:97] offset:8192
	v_mul_f32_e32 v140, 0xbfb8aa3b, v92
	v_mul_f32_e32 v141, 0xbfb8aa3b, v93
	v_mul_f32_e32 v142, 0xbfb8aa3b, v94
	v_mul_f32_e32 v143, 0xbfb8aa3b, v95
; DEV u32x2 pk4(f32x4 v) { u32x2 r = {pk_bf16(v[0], v[1]), pk_bf16(v[2], v[3])}; return r; }
; DEV float fsigmoid(float x) { return 1.f / (1.f + __expf(-x)); }
;   DEV void operator()(f32x4 (&acc)[2][2][4][2], int brow, int bcol, int wr, int wc, int fr, int fq) const {
;     ...
;     for (int ai = 0; ai < 2; ++ai)
; #pragma unroll
;       for (int m = 0; m < 4; ++m) {
;         const int rl = ai * 128 + wr * 64 + m * 16 + fr, tok = brow + rl;
; #pragma unroll
;         for (int bj = 0; bj < 2; ++bj)
; #pragma unroll
;           for (int n = 0; n < 2; ++n) {
;             const int cl = bj * 128 + wc * 32 + n * 16 + fq * 4, lc = bcol - segstart + cl;
;             f32x4 v = acc[ai][bj][m][n];
;             if (mode == 0) {
;               tile_put4(rl, cl, pk4(v * scale));
;             } else if (mode == 1) {
;               for (int j = 0; j < 4; ++j) v[j] = v[j] * fsigmoid(v[j]);
;               tile_put4(rl, cl, pk4(v));
	v_exp_f32_e32 v140, v140
	v_exp_f32_e32 v141, v141
	v_exp_f32_e32 v142, v142
	v_exp_f32_e32 v143, v143
	v_pk_add_f32 v[140:141], v[140:141], 1.0 op_sel_hi:[1,0]
	v_pk_add_f32 v[142:143], v[142:143], 1.0 op_sel_hi:[1,0]
	v_rcp_f32_e32 v140, v140
	v_rcp_f32_e32 v141, v141
	v_rcp_f32_e32 v142, v142
	v_rcp_f32_e32 v143, v143
	v_pk_mul_f32 v[92:93], v[92:93], v[140:141]
	v_pk_mul_f32 v[94:95], v[94:95], v[142:143]
	v_cvt_pk_bf16_f32 v92, v92, v93
	v_cvt_pk_bf16_f32 v93, v94, v95
	ds_write_b64 v134, v[92:93] offset:16384
	v_mul_f32_e32 v144, 0xbfb8aa3b, v88
	v_mul_f32_e32 v145, 0xbfb8aa3b, v89
	v_mul_f32_e32 v146, 0xbfb8aa3b, v90
	v_mul_f32_e32 v147, 0xbfb8aa3b, v91
	v_exp_f32_e32 v144, v144
	v_exp_f32_e32 v145, v145
	v_exp_f32_e32 v146, v146
	v_exp_f32_e32 v147, v147
	v_pk_add_f32 v[144:145], v[144:145], 1.0 op_sel_hi:[1,0]
	v_pk_add_f32 v[146:147], v[146:147], 1.0 op_sel_hi:[1,0]
	v_rcp_f32_e32 v144, v144
	v_rcp_f32_e32 v145, v145
	v_rcp_f32_e32 v146, v146
	v_rcp_f32_e32 v147, v147
	v_pk_mul_f32 v[88:89], v[88:89], v[144:145]
	v_pk_mul_f32 v[90:91], v[90:91], v[146:147]
	v_cvt_pk_bf16_f32 v88, v88, v89
	v_cvt_pk_bf16_f32 v89, v90, v91
	ds_write_b64 v135, v[88:89] offset:16384
	v_mul_f32_e32 v140, 0xbfb8aa3b, v84
	v_mul_f32_e32 v141, 0xbfb8aa3b, v85
	v_mul_f32_e32 v142, 0xbfb8aa3b, v86
	v_mul_f32_e32 v143, 0xbfb8aa3b, v87
	v_exp_f32_e32 v140, v140
	v_exp_f32_e32 v141, v141
	v_exp_f32_e32 v142, v142
	v_exp_f32_e32 v143, v143
	v_pk_add_f32 v[140:141], v[140:141], 1.0 op_sel_hi:[1,0]
	v_pk_add_f32 v[142:143], v[142:143], 1.0 op_sel_hi:[1,0]
	v_rcp_f32_e32 v140, v140
	v_rcp_f32_e32 v141, v141
	v_rcp_f32_e32 v142, v142
	v_rcp_f32_e32 v143, v143
	v_pk_mul_f32 v[84:85], v[84:85], v[140:141]
	v_pk_mul_f32 v[86:87], v[86:87], v[142:143]
	v_cvt_pk_bf16_f32 v84, v84, v85
	v_cvt_pk_bf16_f32 v85, v86, v87
	ds_write_b64 v134, v[84:85] offset:16640
	v_mul_f32_e32 v144, 0xbfb8aa3b, v80
	v_mul_f32_e32 v145, 0xbfb8aa3b, v81
	v_mul_f32_e32 v146, 0xbfb8aa3b, v82
	v_mul_f32_e32 v147, 0xbfb8aa3b, v83
	v_exp_f32_e32 v144, v144
	v_exp_f32_e32 v145, v145
	v_exp_f32_e32 v146, v146
	v_exp_f32_e32 v147, v147
	v_pk_add_f32 v[144:145], v[144:145], 1.0 op_sel_hi:[1,0]
	v_pk_add_f32 v[146:147], v[146:147], 1.0 op_sel_hi:[1,0]
	v_rcp_f32_e32 v144, v144
	v_rcp_f32_e32 v145, v145
	v_rcp_f32_e32 v146, v146
	v_rcp_f32_e32 v147, v147
	v_pk_mul_f32 v[80:81], v[80:81], v[144:145]
	v_pk_mul_f32 v[82:83], v[82:83], v[146:147]
	v_cvt_pk_bf16_f32 v80, v80, v81
	v_cvt_pk_bf16_f32 v81, v82, v83
	ds_write_b64 v135, v[80:81] offset:16640
	v_mul_f32_e32 v140, 0xbfb8aa3b, v76
	v_mul_f32_e32 v141, 0xbfb8aa3b, v77
	v_mul_f32_e32 v142, 0xbfb8aa3b, v78
	v_mul_f32_e32 v143, 0xbfb8aa3b, v79
	v_exp_f32_e32 v140, v140
	v_exp_f32_e32 v141, v141
	v_exp_f32_e32 v142, v142
	v_exp_f32_e32 v143, v143
	v_pk_add_f32 v[140:141], v[140:141], 1.0 op_sel_hi:[1,0]
	v_pk_add_f32 v[142:143], v[142:143], 1.0 op_sel_hi:[1,0]
	v_rcp_f32_e32 v140, v140
	v_rcp_f32_e32 v141, v141
	v_rcp_f32_e32 v142, v142
	v_rcp_f32_e32 v143, v143
	v_pk_mul_f32 v[76:77], v[76:77], v[140:141]
	v_pk_mul_f32 v[78:79], v[78:79], v[142:143]
	v_cvt_pk_bf16_f32 v76, v76, v77
	v_cvt_pk_bf16_f32 v77, v78, v79
	ds_write_b64 v134, v[76:77] offset:24832
	v_mul_f32_e32 v144, 0xbfb8aa3b, v72
	v_mul_f32_e32 v145, 0xbfb8aa3b, v73
	v_mul_f32_e32 v146, 0xbfb8aa3b, v74
	v_mul_f32_e32 v147, 0xbfb8aa3b, v75
	v_exp_f32_e32 v144, v144
	v_exp_f32_e32 v145, v145
	v_exp_f32_e32 v146, v146
	v_exp_f32_e32 v147, v147
	v_pk_add_f32 v[144:145], v[144:145], 1.0 op_sel_hi:[1,0]
	v_pk_add_f32 v[146:147], v[146:147], 1.0 op_sel_hi:[1,0]
	v_rcp_f32_e32 v144, v144
	v_rcp_f32_e32 v145, v145
	v_rcp_f32_e32 v146, v146
	v_rcp_f32_e32 v147, v147
	v_pk_mul_f32 v[72:73], v[72:73], v[144:145]
	v_pk_mul_f32 v[74:75], v[74:75], v[146:147]
	v_cvt_pk_bf16_f32 v72, v72, v73
	v_cvt_pk_bf16_f32 v73, v74, v75
	ds_write_b64 v135, v[72:73] offset:24832
	v_mul_f32_e32 v140, 0xbfb8aa3b, v68
	v_mul_f32_e32 v141, 0xbfb8aa3b, v69
	v_mul_f32_e32 v142, 0xbfb8aa3b, v70
	v_mul_f32_e32 v143, 0xbfb8aa3b, v71
	v_exp_f32_e32 v140, v140
	v_exp_f32_e32 v141, v141
	v_exp_f32_e32 v142, v142
	v_exp_f32_e32 v143, v143
	v_pk_add_f32 v[140:141], v[140:141], 1.0 op_sel_hi:[1,0]
	v_pk_add_f32 v[142:143], v[142:143], 1.0 op_sel_hi:[1,0]
	v_rcp_f32_e32 v140, v140
	v_rcp_f32_e32 v141, v141
	v_rcp_f32_e32 v142, v142
	v_rcp_f32_e32 v143, v143
	v_pk_mul_f32 v[68:69], v[68:69], v[140:141]
	v_pk_mul_f32 v[70:71], v[70:71], v[142:143]
	v_cvt_pk_bf16_f32 v68, v68, v69
	v_cvt_pk_bf16_f32 v69, v70, v71
	ds_write_b64 v134, v[68:69] offset:24576
	v_mul_f32_e32 v144, 0xbfb8aa3b, v64
	v_mul_f32_e32 v145, 0xbfb8aa3b, v65
	v_mul_f32_e32 v146, 0xbfb8aa3b, v66
	v_mul_f32_e32 v147, 0xbfb8aa3b, v67
	v_exp_f32_e32 v144, v144
	v_exp_f32_e32 v145, v145
	v_exp_f32_e32 v146, v146
	v_exp_f32_e32 v147, v147
	v_pk_add_f32 v[144:145], v[144:145], 1.0 op_sel_hi:[1,0]
	v_pk_add_f32 v[146:147], v[146:147], 1.0 op_sel_hi:[1,0]
	v_rcp_f32_e32 v144, v144
	v_rcp_f32_e32 v145, v145
	v_rcp_f32_e32 v146, v146
	v_rcp_f32_e32 v147, v147
	v_pk_mul_f32 v[64:65], v[64:65], v[144:145]
	v_pk_mul_f32 v[66:67], v[66:67], v[146:147]
	v_cvt_pk_bf16_f32 v64, v64, v65
	v_cvt_pk_bf16_f32 v65, v66, v67
	ds_write_b64 v135, v[64:65] offset:24576
	v_mul_f32_e32 v140, 0xbfb8aa3b, v60
	v_mul_f32_e32 v141, 0xbfb8aa3b, v61
	v_mul_f32_e32 v142, 0xbfb8aa3b, v62
	v_mul_f32_e32 v143, 0xbfb8aa3b, v63
	v_exp_f32_e32 v140, v140
	v_exp_f32_e32 v141, v141
	v_exp_f32_e32 v142, v142
	v_exp_f32_e32 v143, v143
	v_pk_add_f32 v[140:141], v[140:141], 1.0 op_sel_hi:[1,0]
	v_pk_add_f32 v[142:143], v[142:143], 1.0 op_sel_hi:[1,0]
	v_rcp_f32_e32 v140, v140
	v_rcp_f32_e32 v141, v141
; DEV u32x2 pk4(f32x4 v) { u32x2 r = {pk_bf16(v[0], v[1]), pk_bf16(v[2], v[3])}; return r; }
; DEV float fsigmoid(float x) { return 1.f / (1.f + __expf(-x)); }
;   DEV void operator()(f32x4 (&acc)[2][2][4][2], int brow, int bcol, int wr, int wc, int fr, int fq) const {
;     ...
;     for (int ai = 0; ai < 2; ++ai)
; #pragma unroll
;       for (int m = 0; m < 4; ++m) {
;         const int rl = ai * 128 + wr * 64 + m * 16 + fr, tok = brow + rl;
; #pragma unroll
;         for (int bj = 0; bj < 2; ++bj)
; #pragma unroll
;           for (int n = 0; n < 2; ++n) {
;             const int cl = bj * 128 + wc * 32 + n * 16 + fq * 4, lc = bcol - segstart + cl;
;             f32x4 v = acc[ai][bj][m][n];
;             if (mode == 0) {
;               tile_put4(rl, cl, pk4(v * scale));
;             } else if (mode == 1) {
;               for (int j = 0; j < 4; ++j) v[j] = v[j] * fsigmoid(v[j]);
;               tile_put4(rl, cl, pk4(v));
	v_rcp_f32_e32 v142, v142
	v_rcp_f32_e32 v143, v143
	v_pk_mul_f32 v[60:61], v[60:61], v[140:141]
	v_pk_mul_f32 v[62:63], v[62:63], v[142:143]
	v_cvt_pk_bf16_f32 v60, v60, v61
	v_cvt_pk_bf16_f32 v61, v62, v63
	ds_write_b64 v136, v[60:61]
	v_mul_f32_e32 v144, 0xbfb8aa3b, v56
	v_mul_f32_e32 v145, 0xbfb8aa3b, v57
	v_mul_f32_e32 v146, 0xbfb8aa3b, v58
	v_mul_f32_e32 v147, 0xbfb8aa3b, v59
	v_exp_f32_e32 v144, v144
	v_exp_f32_e32 v145, v145
	v_exp_f32_e32 v146, v146
	v_exp_f32_e32 v147, v147
	v_pk_add_f32 v[144:145], v[144:145], 1.0 op_sel_hi:[1,0]
	v_pk_add_f32 v[146:147], v[146:147], 1.0 op_sel_hi:[1,0]
	v_rcp_f32_e32 v144, v144
	v_rcp_f32_e32 v145, v145
	v_rcp_f32_e32 v146, v146
	v_rcp_f32_e32 v147, v147
	v_pk_mul_f32 v[56:57], v[56:57], v[144:145]
	v_pk_mul_f32 v[58:59], v[58:59], v[146:147]
	v_cvt_pk_bf16_f32 v56, v56, v57
	v_cvt_pk_bf16_f32 v57, v58, v59
	ds_write_b64 v137, v[56:57]
	v_mul_f32_e32 v140, 0xbfb8aa3b, v52
	v_mul_f32_e32 v141, 0xbfb8aa3b, v53
	v_mul_f32_e32 v142, 0xbfb8aa3b, v54
	v_mul_f32_e32 v143, 0xbfb8aa3b, v55
	v_exp_f32_e32 v140, v140
	v_exp_f32_e32 v141, v141
	v_exp_f32_e32 v142, v142
	v_exp_f32_e32 v143, v143
	v_pk_add_f32 v[140:141], v[140:141], 1.0 op_sel_hi:[1,0]
	v_pk_add_f32 v[142:143], v[142:143], 1.0 op_sel_hi:[1,0]
	v_rcp_f32_e32 v140, v140
	v_rcp_f32_e32 v141, v141
	v_rcp_f32_e32 v142, v142
	v_rcp_f32_e32 v143, v143
	v_pk_mul_f32 v[52:53], v[52:53], v[140:141]
	v_pk_mul_f32 v[54:55], v[54:55], v[142:143]
	v_cvt_pk_bf16_f32 v52, v52, v53
	v_cvt_pk_bf16_f32 v53, v54, v55
	ds_write_b64 v136, v[52:53] offset:256
	v_mul_f32_e32 v144, 0xbfb8aa3b, v48
	v_mul_f32_e32 v145, 0xbfb8aa3b, v49
	v_mul_f32_e32 v146, 0xbfb8aa3b, v50
	v_mul_f32_e32 v147, 0xbfb8aa3b, v51
	v_exp_f32_e32 v144, v144
	v_exp_f32_e32 v145, v145
	v_exp_f32_e32 v146, v146
	v_exp_f32_e32 v147, v147
	v_pk_add_f32 v[144:145], v[144:145], 1.0 op_sel_hi:[1,0]
	v_pk_add_f32 v[146:147], v[146:147], 1.0 op_sel_hi:[1,0]
	v_rcp_f32_e32 v144, v144
	v_rcp_f32_e32 v145, v145
	v_rcp_f32_e32 v146, v146
	v_rcp_f32_e32 v147, v147
	v_pk_mul_f32 v[48:49], v[48:49], v[144:145]
	v_pk_mul_f32 v[50:51], v[50:51], v[146:147]
	v_cvt_pk_bf16_f32 v48, v48, v49
	v_cvt_pk_bf16_f32 v49, v50, v51
	ds_write_b64 v137, v[48:49] offset:256
	v_mul_f32_e32 v140, 0xbfb8aa3b, v44
	v_mul_f32_e32 v141, 0xbfb8aa3b, v45
	v_mul_f32_e32 v142, 0xbfb8aa3b, v46
	v_mul_f32_e32 v143, 0xbfb8aa3b, v47
	v_exp_f32_e32 v140, v140
	v_exp_f32_e32 v141, v141
	v_exp_f32_e32 v142, v142
	v_exp_f32_e32 v143, v143
	v_pk_add_f32 v[140:141], v[140:141], 1.0 op_sel_hi:[1,0]
	v_pk_add_f32 v[142:143], v[142:143], 1.0 op_sel_hi:[1,0]
	v_rcp_f32_e32 v140, v140
	v_rcp_f32_e32 v141, v141
	v_rcp_f32_e32 v142, v142
	v_rcp_f32_e32 v143, v143
	v_pk_mul_f32 v[44:45], v[44:45], v[140:141]
	v_pk_mul_f32 v[46:47], v[46:47], v[142:143]
	v_cvt_pk_bf16_f32 v44, v44, v45
	v_cvt_pk_bf16_f32 v45, v46, v47
	ds_write_b64 v136, v[44:45] offset:8448
	v_mul_f32_e32 v144, 0xbfb8aa3b, v40
	v_mul_f32_e32 v145, 0xbfb8aa3b, v41
	v_mul_f32_e32 v146, 0xbfb8aa3b, v42
	v_mul_f32_e32 v147, 0xbfb8aa3b, v43
	v_exp_f32_e32 v144, v144
	v_exp_f32_e32 v145, v145
	v_exp_f32_e32 v146, v146
	v_exp_f32_e32 v147, v147
	v_pk_add_f32 v[144:145], v[144:145], 1.0 op_sel_hi:[1,0]
	v_pk_add_f32 v[146:147], v[146:147], 1.0 op_sel_hi:[1,0]
	v_rcp_f32_e32 v144, v144
	v_rcp_f32_e32 v145, v145
	v_rcp_f32_e32 v146, v146
	v_rcp_f32_e32 v147, v147
	v_pk_mul_f32 v[40:41], v[40:41], v[144:145]
	v_pk_mul_f32 v[42:43], v[42:43], v[146:147]
	v_cvt_pk_bf16_f32 v40, v40, v41
	v_cvt_pk_bf16_f32 v41, v42, v43
	ds_write_b64 v137, v[40:41] offset:8448
	v_mul_f32_e32 v140, 0xbfb8aa3b, v36
	v_mul_f32_e32 v141, 0xbfb8aa3b, v37
	v_mul_f32_e32 v142, 0xbfb8aa3b, v38
	v_mul_f32_e32 v143, 0xbfb8aa3b, v39
	v_exp_f32_e32 v140, v140
	v_exp_f32_e32 v141, v141
	v_exp_f32_e32 v142, v142
	v_exp_f32_e32 v143, v143
	v_pk_add_f32 v[140:141], v[140:141], 1.0 op_sel_hi:[1,0]
	v_pk_add_f32 v[142:143], v[142:143], 1.0 op_sel_hi:[1,0]
	v_rcp_f32_e32 v140, v140
	v_rcp_f32_e32 v141, v141
	v_rcp_f32_e32 v142, v142
	v_rcp_f32_e32 v143, v143
	v_pk_mul_f32 v[36:37], v[36:37], v[140:141]
	v_pk_mul_f32 v[38:39], v[38:39], v[142:143]
	v_cvt_pk_bf16_f32 v36, v36, v37
	v_cvt_pk_bf16_f32 v37, v38, v39
	ds_write_b64 v136, v[36:37] offset:8192
	v_mul_f32_e32 v144, 0xbfb8aa3b, v32
	v_mul_f32_e32 v145, 0xbfb8aa3b, v33
	v_mul_f32_e32 v146, 0xbfb8aa3b, v34
	v_mul_f32_e32 v147, 0xbfb8aa3b, v35
	v_exp_f32_e32 v144, v144
	v_exp_f32_e32 v145, v145
	v_exp_f32_e32 v146, v146
	v_exp_f32_e32 v147, v147
	v_pk_add_f32 v[144:145], v[144:145], 1.0 op_sel_hi:[1,0]
	v_pk_add_f32 v[146:147], v[146:147], 1.0 op_sel_hi:[1,0]
	v_rcp_f32_e32 v144, v144
	v_rcp_f32_e32 v145, v145
	v_rcp_f32_e32 v146, v146
	v_rcp_f32_e32 v147, v147
	v_pk_mul_f32 v[32:33], v[32:33], v[144:145]
	v_pk_mul_f32 v[34:35], v[34:35], v[146:147]
	v_cvt_pk_bf16_f32 v32, v32, v33
	v_cvt_pk_bf16_f32 v33, v34, v35
	ds_write_b64 v137, v[32:33] offset:8192
	v_mul_f32_e32 v140, 0xbfb8aa3b, v28
	v_mul_f32_e32 v141, 0xbfb8aa3b, v29
	v_mul_f32_e32 v142, 0xbfb8aa3b, v30
	v_mul_f32_e32 v143, 0xbfb8aa3b, v31
	v_exp_f32_e32 v140, v140
	v_exp_f32_e32 v141, v141
	v_exp_f32_e32 v142, v142
	v_exp_f32_e32 v143, v143
	v_pk_add_f32 v[140:141], v[140:141], 1.0 op_sel_hi:[1,0]
	v_pk_add_f32 v[142:143], v[142:143], 1.0 op_sel_hi:[1,0]
	v_rcp_f32_e32 v140, v140
	v_rcp_f32_e32 v141, v141
	v_rcp_f32_e32 v142, v142
	v_rcp_f32_e32 v143, v143
	v_pk_mul_f32 v[28:29], v[28:29], v[140:141]
	v_pk_mul_f32 v[30:31], v[30:31], v[142:143]
	v_cvt_pk_bf16_f32 v28, v28, v29
	v_cvt_pk_bf16_f32 v29, v30, v31
	ds_write_b64 v136, v[28:29] offset:16384
	v_mul_f32_e32 v144, 0xbfb8aa3b, v24
	v_mul_f32_e32 v145, 0xbfb8aa3b, v25
; DEV u32x2 pk4(f32x4 v) { u32x2 r = {pk_bf16(v[0], v[1]), pk_bf16(v[2], v[3])}; return r; }
; DEV float fsigmoid(float x) { return 1.f / (1.f + __expf(-x)); }
;   DEV void operator()(f32x4 (&acc)[2][2][4][2], int brow, int bcol, int wr, int wc, int fr, int fq) const {
;     ...
;     for (int ai = 0; ai < 2; ++ai)
; #pragma unroll
;       for (int m = 0; m < 4; ++m) {
;         const int rl = ai * 128 + wr * 64 + m * 16 + fr, tok = brow + rl;
; #pragma unroll
;         for (int bj = 0; bj < 2; ++bj)
; #pragma unroll
;           for (int n = 0; n < 2; ++n) {
;             const int cl = bj * 128 + wc * 32 + n * 16 + fq * 4, lc = bcol - segstart + cl;
;             f32x4 v = acc[ai][bj][m][n];
;             if (mode == 0) {
;               tile_put4(rl, cl, pk4(v * scale));
;             } else if (mode == 1) {
;               for (int j = 0; j < 4; ++j) v[j] = v[j] * fsigmoid(v[j]);
;               tile_put4(rl, cl, pk4(v));
	v_mul_f32_e32 v146, 0xbfb8aa3b, v26
	v_mul_f32_e32 v147, 0xbfb8aa3b, v27
	v_exp_f32_e32 v144, v144
	v_exp_f32_e32 v145, v145
	v_exp_f32_e32 v146, v146
	v_exp_f32_e32 v147, v147
	v_pk_add_f32 v[144:145], v[144:145], 1.0 op_sel_hi:[1,0]
	v_pk_add_f32 v[146:147], v[146:147], 1.0 op_sel_hi:[1,0]
	v_rcp_f32_e32 v144, v144
	v_rcp_f32_e32 v145, v145
	v_rcp_f32_e32 v146, v146
	v_rcp_f32_e32 v147, v147
	v_pk_mul_f32 v[24:25], v[24:25], v[144:145]
	v_pk_mul_f32 v[26:27], v[26:27], v[146:147]
	v_cvt_pk_bf16_f32 v24, v24, v25
	v_cvt_pk_bf16_f32 v25, v26, v27
	ds_write_b64 v137, v[24:25] offset:16384
	v_mul_f32_e32 v140, 0xbfb8aa3b, v20
	v_mul_f32_e32 v141, 0xbfb8aa3b, v21
	v_mul_f32_e32 v142, 0xbfb8aa3b, v22
	v_mul_f32_e32 v143, 0xbfb8aa3b, v23
	v_exp_f32_e32 v140, v140
	v_exp_f32_e32 v141, v141
	v_exp_f32_e32 v142, v142
	v_exp_f32_e32 v143, v143
	v_pk_add_f32 v[140:141], v[140:141], 1.0 op_sel_hi:[1,0]
	v_pk_add_f32 v[142:143], v[142:143], 1.0 op_sel_hi:[1,0]
	v_rcp_f32_e32 v140, v140
	v_rcp_f32_e32 v141, v141
	v_rcp_f32_e32 v142, v142
	v_rcp_f32_e32 v143, v143
	v_pk_mul_f32 v[20:21], v[20:21], v[140:141]
	v_pk_mul_f32 v[22:23], v[22:23], v[142:143]
	v_cvt_pk_bf16_f32 v20, v20, v21
	v_cvt_pk_bf16_f32 v21, v22, v23
	ds_write_b64 v136, v[20:21] offset:16640
	v_mul_f32_e32 v144, 0xbfb8aa3b, v16
	v_mul_f32_e32 v145, 0xbfb8aa3b, v17
	v_mul_f32_e32 v146, 0xbfb8aa3b, v18
	v_mul_f32_e32 v147, 0xbfb8aa3b, v19
	v_exp_f32_e32 v144, v144
	v_exp_f32_e32 v145, v145
	v_exp_f32_e32 v146, v146
	v_exp_f32_e32 v147, v147
	v_pk_add_f32 v[144:145], v[144:145], 1.0 op_sel_hi:[1,0]
	v_pk_add_f32 v[146:147], v[146:147], 1.0 op_sel_hi:[1,0]
	v_rcp_f32_e32 v144, v144
	v_rcp_f32_e32 v145, v145
	v_rcp_f32_e32 v146, v146
	v_rcp_f32_e32 v147, v147
	v_pk_mul_f32 v[16:17], v[16:17], v[144:145]
	v_pk_mul_f32 v[18:19], v[18:19], v[146:147]
	v_cvt_pk_bf16_f32 v16, v16, v17
	v_cvt_pk_bf16_f32 v17, v18, v19
	ds_write_b64 v137, v[16:17] offset:16640
	v_mul_f32_e32 v140, 0xbfb8aa3b, v12
	v_mul_f32_e32 v141, 0xbfb8aa3b, v13
	v_mul_f32_e32 v142, 0xbfb8aa3b, v14
	v_mul_f32_e32 v143, 0xbfb8aa3b, v15
	v_exp_f32_e32 v140, v140
	v_exp_f32_e32 v141, v141
	v_exp_f32_e32 v142, v142
	v_exp_f32_e32 v143, v143
	v_pk_add_f32 v[140:141], v[140:141], 1.0 op_sel_hi:[1,0]
	v_pk_add_f32 v[142:143], v[142:143], 1.0 op_sel_hi:[1,0]
	v_rcp_f32_e32 v140, v140
	v_rcp_f32_e32 v141, v141
	v_rcp_f32_e32 v142, v142
	v_rcp_f32_e32 v143, v143
	v_pk_mul_f32 v[12:13], v[12:13], v[140:141]
	v_pk_mul_f32 v[14:15], v[14:15], v[142:143]
	v_cvt_pk_bf16_f32 v12, v12, v13
	v_cvt_pk_bf16_f32 v13, v14, v15
	ds_write_b64 v136, v[12:13] offset:24832
	v_mul_f32_e32 v144, 0xbfb8aa3b, v8
	v_mul_f32_e32 v145, 0xbfb8aa3b, v9
	v_mul_f32_e32 v146, 0xbfb8aa3b, v10
	v_mul_f32_e32 v147, 0xbfb8aa3b, v11
	v_exp_f32_e32 v144, v144
	v_exp_f32_e32 v145, v145
	v_exp_f32_e32 v146, v146
	v_exp_f32_e32 v147, v147
	v_pk_add_f32 v[144:145], v[144:145], 1.0 op_sel_hi:[1,0]
	v_pk_add_f32 v[146:147], v[146:147], 1.0 op_sel_hi:[1,0]
	v_rcp_f32_e32 v144, v144
	v_rcp_f32_e32 v145, v145
	v_rcp_f32_e32 v146, v146
	v_rcp_f32_e32 v147, v147
	v_pk_mul_f32 v[8:9], v[8:9], v[144:145]
	v_pk_mul_f32 v[10:11], v[10:11], v[146:147]
	v_cvt_pk_bf16_f32 v8, v8, v9
	v_cvt_pk_bf16_f32 v9, v10, v11
	ds_write_b64 v137, v[8:9] offset:24832
	v_mul_f32_e32 v140, 0xbfb8aa3b, v4
	v_mul_f32_e32 v141, 0xbfb8aa3b, v5
	v_mul_f32_e32 v142, 0xbfb8aa3b, v6
	v_mul_f32_e32 v143, 0xbfb8aa3b, v7
	v_exp_f32_e32 v140, v140
	v_exp_f32_e32 v141, v141
	v_exp_f32_e32 v142, v142
	v_exp_f32_e32 v143, v143
	v_pk_add_f32 v[140:141], v[140:141], 1.0 op_sel_hi:[1,0]
	v_pk_add_f32 v[142:143], v[142:143], 1.0 op_sel_hi:[1,0]
	v_rcp_f32_e32 v140, v140
	v_rcp_f32_e32 v141, v141
	v_rcp_f32_e32 v142, v142
	v_rcp_f32_e32 v143, v143
	v_pk_mul_f32 v[4:5], v[4:5], v[140:141]
	v_pk_mul_f32 v[6:7], v[6:7], v[142:143]
	v_cvt_pk_bf16_f32 v4, v4, v5
	v_cvt_pk_bf16_f32 v5, v6, v7
	ds_write_b64 v136, v[4:5] offset:24576
	v_mul_f32_e32 v144, 0xbfb8aa3b, v0
	v_mul_f32_e32 v145, 0xbfb8aa3b, v1
	v_mul_f32_e32 v146, 0xbfb8aa3b, v2
	v_mul_f32_e32 v147, 0xbfb8aa3b, v3
	v_exp_f32_e32 v144, v144
	v_exp_f32_e32 v145, v145
	v_exp_f32_e32 v146, v146
	v_exp_f32_e32 v147, v147
	v_pk_add_f32 v[144:145], v[144:145], 1.0 op_sel_hi:[1,0]
	v_pk_add_f32 v[146:147], v[146:147], 1.0 op_sel_hi:[1,0]
	v_rcp_f32_e32 v144, v144
	v_rcp_f32_e32 v145, v145
	v_rcp_f32_e32 v146, v146
	v_rcp_f32_e32 v147, v147
	v_pk_mul_f32 v[0:1], v[0:1], v[144:145]
	v_pk_mul_f32 v[2:3], v[2:3], v[146:147]
	v_cvt_pk_bf16_f32 v0, v0, v1
	v_cvt_pk_bf16_f32 v1, v2, v3
	ds_write_b64 v137, v[0:1] offset:24576
; DEV u32x2 pk4(f32x4 v) { u32x2 r = {pk_bf16(v[0], v[1]), pk_bf16(v[2], v[3])}; return r; }
; DEV int sig4(int x) { return ((x & 1) << 1) | (x >> 1); }
; template <bool NT = false>
; DEV void tile_rows_out(bf16_t* __restrict__ out0, const size_t ld, const int tid) {
; #pragma unroll
;   for (int i = 0; i < 16; ++i) {
;     const int id = i * 512 + tid, r = id >> 5, pos = id & 31, c = pos ^ (r & 31);
;     const u32x4 v = *(const u32x4*)(smem + r * 512 + pos * 16);
;     if (NT) __builtin_nontemporal_store(v, (u32x4*)(out0 + (size_t)r * ld + 8 * c)); else *(u32x4*)(out0 + (size_t)r * ld + 8 * c) = v;
;   }
;   DEV void operator()(f32x4 (&acc)[2][2][4][2], int brow, int bcol, int wr, int wc, int fr, int fq) const {
;     ...
;               const f32x4 b4 = *(const f32x4*)(bmat + (size_t)tok * 1024 + lc);
;               const int pcl = (cl & ~15) + 4 * sig4((cl >> 2) & 3);
;               if (mode == 3) {
;                 for (int j = 0; j < 4; ++j) v[j] = v[j] * scale * __expf(b4[j]);
;                 tile_put4(rl, pcl, pk4(v));
;               } else {
;                 const f32x4 bl = *(const f32x4*)(bmat + (size_t)(tok | 63) * 1024 + lc);
.Lepi_lean_rows:
	s_mul_i32 s0, s4, s8
	s_sub_i32 s1, s6, s36
	s_add_i32 s0, s0, s1
	s_ashr_i32 s1, s0, 31
	s_lshl_b64 s[0:1], s[0:1], 1
	s_add_u32 s0, s14, s0
	s_addc_u32 s1, s15, s1
	v_lshrrev_b32_e32 v138, 5, v198
	v_and_b32_e32 v139, 31, v198
	v_xor_b32_e32 v139, v139, v138
	v_mul_lo_u32 v140, v138, s8
	v_lshlrev_b32_e32 v140, 1, v140
	v_lshl_add_u32 v141, v139, 4, v140
	v_xor_b32_e32 v139, 16, v139
	v_lshl_add_u32 v142, v139, 4, v140
	s_lshl_b32 s5, s8, 5
	v_add_u32_e32 v142, s5, v142
	s_lshl_b32 s5, s8, 6
	v_lshlrev_b32_e32 v143, 4, v198
	v_add_u32_e32 v144, 0x10000, v143
	s_waitcnt lgkmcnt(0)
	s_barrier
	ds_read_b128 v[0:3], v143
	ds_read_b128 v[4:7], v143 offset:8192
	ds_read_b128 v[8:11], v143 offset:16384
	ds_read_b128 v[12:15], v143 offset:24576
	ds_read_b128 v[16:19], v143 offset:32768
	ds_read_b128 v[20:23], v143 offset:40960
	ds_read_b128 v[24:27], v143 offset:49152
	ds_read_b128 v[28:31], v143 offset:57344
	ds_read_b128 v[32:35], v144
	ds_read_b128 v[36:39], v144 offset:8192
	ds_read_b128 v[40:43], v144 offset:16384
	ds_read_b128 v[44:47], v144 offset:24576
	ds_read_b128 v[48:51], v144 offset:32768
	ds_read_b128 v[52:55], v144 offset:40960
	ds_read_b128 v[56:59], v144 offset:49152
	ds_read_b128 v[60:63], v144 offset:57344
	s_waitcnt lgkmcnt(15)
	global_store_dwordx4 v141, v[0:3], s[0:1] nt
	v_add_u32_e32 v141, s5, v141
	s_waitcnt lgkmcnt(14)
	global_store_dwordx4 v142, v[4:7], s[0:1] nt
	v_add_u32_e32 v142, s5, v142
	s_waitcnt lgkmcnt(13)
	global_store_dwordx4 v141, v[8:11], s[0:1] nt
	v_add_u32_e32 v141, s5, v141
	s_waitcnt lgkmcnt(12)
	global_store_dwordx4 v142, v[12:15], s[0:1] nt
	v_add_u32_e32 v142, s5, v142
	s_waitcnt lgkmcnt(11)
	global_store_dwordx4 v141, v[16:19], s[0:1] nt
	v_add_u32_e32 v141, s5, v141
	s_waitcnt lgkmcnt(10)
	global_store_dwordx4 v142, v[20:23], s[0:1] nt
	v_add_u32_e32 v142, s5, v142
	s_waitcnt lgkmcnt(9)
	global_store_dwordx4 v141, v[24:27], s[0:1] nt
	v_add_u32_e32 v141, s5, v141
	s_waitcnt lgkmcnt(8)
	global_store_dwordx4 v142, v[28:31], s[0:1] nt
	v_add_u32_e32 v142, s5, v142
	s_waitcnt lgkmcnt(7)
	global_store_dwordx4 v141, v[32:35], s[0:1] nt
	v_add_u32_e32 v141, s5, v141
	s_waitcnt lgkmcnt(6)
	global_store_dwordx4 v142, v[36:39], s[0:1] nt
	v_add_u32_e32 v142, s5, v142
	s_waitcnt lgkmcnt(5)
	global_store_dwordx4 v141, v[40:43], s[0:1] nt
	v_add_u32_e32 v141, s5, v141
	s_waitcnt lgkmcnt(4)
	global_store_dwordx4 v142, v[44:47], s[0:1] nt
	v_add_u32_e32 v142, s5, v142
	s_waitcnt lgkmcnt(3)
	global_store_dwordx4 v141, v[48:51], s[0:1] nt
	v_add_u32_e32 v141, s5, v141
	s_waitcnt lgkmcnt(2)
	global_store_dwordx4 v142, v[52:55], s[0:1] nt
	v_add_u32_e32 v142, s5, v142
	s_waitcnt lgkmcnt(1)
	global_store_dwordx4 v141, v[56:59], s[0:1] nt
	s_waitcnt lgkmcnt(0)
	global_store_dwordx4 v142, v[60:63], s[0:1] nt
	s_branch .LBB0_1555
.Lepi_orig34:
	s_cmp_lt_i32 s37, 3
	s_cbranch_scc1 .Lp1_nopf
	v_readlane_b32 s20, v253, 54
	v_readlane_b32 s21, v253, 55
	v_ashrrev_i32_e32 v175, 2, v198
	v_and_b32_e32 v174, 15, v198
	v_and_b32_e32 v175, 0xffffffc0, v175
	v_or_b32_e32 v175, v175, v174
	v_add_u32_e32 v175, s4, v175
	v_lshlrev_b32_e32 v175, 12, v175
	v_bfe_u32 v174, v198, 6, 2
	v_lshlrev_b32_e32 v174, 5, v174
	v_add_u32_e32 v174, s6, v174
	v_subrev_u32_e32 v174, s36, v174
	v_lshl_add_u32 v175, v174, 2, v175
	v_bfe_u32 v174, v198, 4, 2
	v_lshl_add_u32 v175, v174, 4, v175
	global_load_dwordx4 v[180:183], v175, s[20:21]
	global_load_dwordx4 v[184:187], v175, s[20:21] offset:64
	global_load_dwordx4 v[188:191], v175, s[20:21] offset:512
	global_load_dwordx4 v[192:195], v175, s[20:21] offset:576
	v_add_u32_e32 v175, 0x10000, v175
	global_load_dwordx4 v[206:209], v175, s[20:21]
	global_load_dwordx4 v[210:213], v175, s[20:21] offset:64
	global_load_dwordx4 v[214:217], v175, s[20:21] offset:512
	global_load_dwordx4 v[224:227], v175, s[20:21] offset:576
	v_add_u32_e32 v175, 0x10000, v175
	global_load_dwordx4 v[228:231], v175, s[20:21]
	global_load_dwordx4 v[232:235], v175, s[20:21] offset:64
	global_load_dwordx4 v[236:239], v175, s[20:21] offset:512
	global_load_dwordx4 v[240:243], v175, s[20:21] offset:576
	v_add_u32_e32 v175, 0x10000, v175
	global_load_dwordx4 v[244:247], v175, s[20:21]
	global_load_dwordx4 v[248:251], v175, s[20:21] offset:64
	global_load_dwordx4 v[166:169], v175, s[20:21] offset:512
	global_load_dwordx4 v[170:173], v175, s[20:21] offset:576
	v_add_u32_e32 v175, 0x10000, v175
